# gla_item decay projection rounds 0..13 rewritten with v_pk_fma_f32 (f32 fused) and rolling LDS prefetch
# speedup vs baseline: 1.0073x; 1.0073x over previous
; #define LAS __attribute__((address_space(3)))
; __device__ void gla_item(const Params& P, int l, int b, int h, int seg, LAS unsigned char* lds) {
;     ...
;             for (int j = 0; j < 8; ++j) x[j] = BUP[d8 + j];
; #pragma unroll
;             for (int r = 0; r < 16; ++r) { const float a = ARAW[t_ * 16 + r]; const f32x4 w0 = *(const LAS f32x4*)(WUP + r * 64 + d8), w1 = *(const LAS f32x4*)(WUP + r * 64 + d8 + 4);
; #pragma unroll
;                 for (int j = 0; j < 4; ++j) { x[j] += a * w0[j]; x[4 + j] += a * w1[j]; } }
.LBB0_484:
	s_waitcnt lgkmcnt(0)
	s_barrier
	ds_read_b128 v[170:173], v119 offset:4096
	ds_read_b128 v[174:177], v119 offset:4112
	ds_read_b128 v[178:181], v139 offset:4352
	ds_read_b128 v[182:185], v139 offset:4368
	ds_read_b128 v[186:189], v139 offset:4384
	ds_read_b128 v[46:49], v139 offset:4400
	ds_read_b128 v[204:207], v119
	ds_read_b128 v[208:211], v119 offset:16
	ds_read_b128 v[212:215], v119 offset:256
	ds_read_b128 v[216:219], v119 offset:272
	ds_read_b128 v[220:223], v119 offset:512
	ds_read_b128 v[224:227], v119 offset:528
	s_waitcnt lgkmcnt(4)
	v_pk_fma_f32 v[170:171], v[178:179], v[204:205], v[170:171] op_sel_hi:[0,1,1]
	v_pk_fma_f32 v[172:173], v[178:179], v[206:207], v[172:173] op_sel_hi:[0,1,1]
	v_pk_fma_f32 v[174:175], v[178:179], v[208:209], v[174:175] op_sel_hi:[0,1,1]
	v_pk_fma_f32 v[176:177], v[178:179], v[210:211], v[176:177] op_sel_hi:[0,1,1]
	ds_read_b128 v[236:239], v119 offset:768
	ds_read_b128 v[240:243], v119 offset:784
	s_waitcnt lgkmcnt(4)
	v_pk_fma_f32 v[170:171], v[178:179], v[212:213], v[170:171] op_sel:[1,0,0]
	v_pk_fma_f32 v[172:173], v[178:179], v[214:215], v[172:173] op_sel:[1,0,0]
	v_pk_fma_f32 v[174:175], v[178:179], v[216:217], v[174:175] op_sel:[1,0,0]
	v_pk_fma_f32 v[176:177], v[178:179], v[218:219], v[176:177] op_sel:[1,0,0]
	ds_read_b128 v[190:193], v119 offset:1024
	ds_read_b128 v[244:247], v119 offset:1040
	s_waitcnt lgkmcnt(4)
	v_pk_fma_f32 v[170:171], v[180:181], v[220:221], v[170:171] op_sel_hi:[0,1,1]
	v_pk_fma_f32 v[172:173], v[180:181], v[222:223], v[172:173] op_sel_hi:[0,1,1]
	v_pk_fma_f32 v[174:175], v[180:181], v[224:225], v[174:175] op_sel_hi:[0,1,1]
	v_pk_fma_f32 v[176:177], v[180:181], v[226:227], v[176:177] op_sel_hi:[0,1,1]
	ds_read_b128 v[204:207], v119 offset:1280
	ds_read_b128 v[208:211], v119 offset:1296
	s_waitcnt lgkmcnt(4)
	v_pk_fma_f32 v[170:171], v[180:181], v[236:237], v[170:171] op_sel:[1,0,0]
	v_pk_fma_f32 v[172:173], v[180:181], v[238:239], v[172:173] op_sel:[1,0,0]
	v_pk_fma_f32 v[174:175], v[180:181], v[240:241], v[174:175] op_sel:[1,0,0]
	v_pk_fma_f32 v[176:177], v[180:181], v[242:243], v[176:177] op_sel:[1,0,0]
	ds_read_b128 v[212:215], v119 offset:1536
	ds_read_b128 v[216:219], v119 offset:1552
	s_waitcnt lgkmcnt(4)
	v_pk_fma_f32 v[170:171], v[182:183], v[190:191], v[170:171] op_sel_hi:[0,1,1]
	v_pk_fma_f32 v[172:173], v[182:183], v[192:193], v[172:173] op_sel_hi:[0,1,1]
	v_pk_fma_f32 v[174:175], v[182:183], v[244:245], v[174:175] op_sel_hi:[0,1,1]
	v_pk_fma_f32 v[176:177], v[182:183], v[246:247], v[176:177] op_sel_hi:[0,1,1]
	ds_read_b128 v[220:223], v119 offset:1792
	ds_read_b128 v[224:227], v119 offset:1808
	s_waitcnt lgkmcnt(4)
	v_pk_fma_f32 v[170:171], v[182:183], v[204:205], v[170:171] op_sel:[1,0,0]
	v_pk_fma_f32 v[172:173], v[182:183], v[206:207], v[172:173] op_sel:[1,0,0]
	v_pk_fma_f32 v[174:175], v[182:183], v[208:209], v[174:175] op_sel:[1,0,0]
	v_pk_fma_f32 v[176:177], v[182:183], v[210:211], v[176:177] op_sel:[1,0,0]
	ds_read_b128 v[236:239], v119 offset:2048
	ds_read_b128 v[240:243], v119 offset:2064
	s_waitcnt lgkmcnt(4)
	v_pk_fma_f32 v[170:171], v[184:185], v[212:213], v[170:171] op_sel_hi:[0,1,1]
	v_pk_fma_f32 v[172:173], v[184:185], v[214:215], v[172:173] op_sel_hi:[0,1,1]
	v_pk_fma_f32 v[174:175], v[184:185], v[216:217], v[174:175] op_sel_hi:[0,1,1]
	v_pk_fma_f32 v[176:177], v[184:185], v[218:219], v[176:177] op_sel_hi:[0,1,1]
	ds_read_b128 v[190:193], v119 offset:2304
	ds_read_b128 v[244:247], v119 offset:2320
	s_waitcnt lgkmcnt(4)
	v_pk_fma_f32 v[170:171], v[184:185], v[220:221], v[170:171] op_sel:[1,0,0]
	v_pk_fma_f32 v[172:173], v[184:185], v[222:223], v[172:173] op_sel:[1,0,0]
	v_pk_fma_f32 v[174:175], v[184:185], v[224:225], v[174:175] op_sel:[1,0,0]
	v_pk_fma_f32 v[176:177], v[184:185], v[226:227], v[176:177] op_sel:[1,0,0]
	ds_read_b128 v[204:207], v119 offset:2560
	ds_read_b128 v[208:211], v119 offset:2576
	s_waitcnt lgkmcnt(4)
	v_pk_fma_f32 v[170:171], v[186:187], v[236:237], v[170:171] op_sel_hi:[0,1,1]
	v_pk_fma_f32 v[172:173], v[186:187], v[238:239], v[172:173] op_sel_hi:[0,1,1]
	v_pk_fma_f32 v[174:175], v[186:187], v[240:241], v[174:175] op_sel_hi:[0,1,1]
	v_pk_fma_f32 v[176:177], v[186:187], v[242:243], v[176:177] op_sel_hi:[0,1,1]
	ds_read_b128 v[212:215], v119 offset:2816
	ds_read_b128 v[216:219], v119 offset:2832
	s_waitcnt lgkmcnt(4)
	v_pk_fma_f32 v[170:171], v[186:187], v[190:191], v[170:171] op_sel:[1,0,0]
	v_pk_fma_f32 v[172:173], v[186:187], v[192:193], v[172:173] op_sel:[1,0,0]
	v_pk_fma_f32 v[174:175], v[186:187], v[244:245], v[174:175] op_sel:[1,0,0]
	v_pk_fma_f32 v[176:177], v[186:187], v[246:247], v[176:177] op_sel:[1,0,0]
	ds_read_b128 v[220:223], v119 offset:3072
	ds_read_b128 v[224:227], v119 offset:3088
	s_waitcnt lgkmcnt(4)
	v_pk_fma_f32 v[170:171], v[188:189], v[204:205], v[170:171] op_sel_hi:[0,1,1]
	v_pk_fma_f32 v[172:173], v[188:189], v[206:207], v[172:173] op_sel_hi:[0,1,1]
	v_pk_fma_f32 v[174:175], v[188:189], v[208:209], v[174:175] op_sel_hi:[0,1,1]
	v_pk_fma_f32 v[176:177], v[188:189], v[210:211], v[176:177] op_sel_hi:[0,1,1]
	ds_read_b128 v[236:239], v119 offset:3328
	ds_read_b128 v[240:243], v119 offset:3344
	s_waitcnt lgkmcnt(4)
	v_pk_fma_f32 v[170:171], v[188:189], v[212:213], v[170:171] op_sel:[1,0,0]
	v_pk_fma_f32 v[172:173], v[188:189], v[214:215], v[172:173] op_sel:[1,0,0]
	v_pk_fma_f32 v[174:175], v[188:189], v[216:217], v[174:175] op_sel:[1,0,0]
	v_pk_fma_f32 v[176:177], v[188:189], v[218:219], v[176:177] op_sel:[1,0,0]
	ds_read_b128 v[50:53], v119 offset:3584
	ds_read_b128 v[54:57], v119 offset:3600
	s_waitcnt lgkmcnt(4)
; #define LAS __attribute__((address_space(3)))
; __device__ __forceinline__ float logsig16(float x) { return (fminf(x, 0.f) - __logf(1.0f + __expf(-fabsf(x)))) * (1.0f / 16.0f); }
; __device__ void gla_item(const Params& P, int l, int b, int h, int seg, LAS unsigned char* lds) {
;     ...
;             for (int j = 0; j < 8; ++j) x[j] = BUP[d8 + j];
; #pragma unroll
;             for (int r = 0; r < 16; ++r) { const float a = ARAW[t_ * 16 + r]; const f32x4 w0 = *(const LAS f32x4*)(WUP + r * 64 + d8), w1 = *(const LAS f32x4*)(WUP + r * 64 + d8 + 4);
; #pragma unroll
;                 for (int j = 0; j < 4; ++j) { x[j] += a * w0[j]; x[4 + j] += a * w1[j]; } }
;             f32x4 o0, o1;
; #pragma unroll
;             for (int j = 0; j < 4; ++j) { o0[j] = logsig16(x[j]); o1[j] = logsig16(x[4 + j]); }
;             *(LAS f32x4*)(LC + t_ * 64 + d8) = o0; *(LAS f32x4*)(LC + t_ * 64 + d8 + 4) = o1;
	v_pk_fma_f32 v[170:171], v[46:47], v[220:221], v[170:171] op_sel_hi:[0,1,1]
	v_pk_fma_f32 v[172:173], v[46:47], v[222:223], v[172:173] op_sel_hi:[0,1,1]
	v_pk_fma_f32 v[174:175], v[46:47], v[224:225], v[174:175] op_sel_hi:[0,1,1]
	v_pk_fma_f32 v[176:177], v[46:47], v[226:227], v[176:177] op_sel_hi:[0,1,1]
	ds_read_b128 v[58:61], v119 offset:3840
	ds_read_b128 v[62:65], v119 offset:3856
	s_waitcnt lgkmcnt(4)
	v_pk_fma_f32 v[170:171], v[46:47], v[236:237], v[170:171] op_sel:[1,0,0]
	v_pk_fma_f32 v[172:173], v[46:47], v[238:239], v[172:173] op_sel:[1,0,0]
	v_pk_fma_f32 v[174:175], v[46:47], v[240:241], v[174:175] op_sel:[1,0,0]
	v_pk_fma_f32 v[176:177], v[46:47], v[242:243], v[176:177] op_sel:[1,0,0]
	v_mov_b32_e32 v155, v170
	v_mov_b32_e32 v69, v171
	v_mov_b32_e32 v157, v172
	v_mov_b32_e32 v159, v173
	v_mov_b32_e32 v68, v174
	v_mov_b32_e32 v156, v175
	v_mov_b32_e32 v158, v176
	v_mov_b32_e32 v66, v177
	s_waitcnt lgkmcnt(2)
	v_mov_b32_e32 v46, v57
	s_waitcnt lgkmcnt(1)
	v_mov_b32_e32 v67, v58
	s_waitcnt lgkmcnt(0)
	v_mov_b32_e32 v47, v65
	v_pk_mul_f32 v[46:47], v[48:49], v[46:47]
	v_mov_b32_e32 v58, v51
	v_add_f32_e32 v46, v66, v46
	v_mov_b32_e32 v66, v50
	v_pk_mul_f32 v[66:67], v[48:49], v[66:67]
	v_mov_b32_e32 v57, v64
	v_add_f32_e32 v50, v155, v66
	v_add_f32_e32 v65, v50, v67
	v_mov_b32_e32 v66, v54
	v_add_f32_e32 v54, v46, v47
	v_mul_f32_e64 v46, |v65|, s3
	v_exp_f32_e32 v46, v46
	v_mov_b32_e32 v67, v62
	v_pk_mul_f32 v[66:67], v[48:49], v[66:67]
	v_mov_b32_e32 v62, v55
	v_add_f32_e32 v46, 1.0, v46
	v_cmp_gt_f32_e32 vcc, s33, v46
	v_add_f32_e32 v50, v68, v66
	v_add_f32_e32 v66, v50, v67
	v_cndmask_b32_e64 v47, 0, 32, vcc
	v_ldexp_f32 v46, v46, v47
	v_log_f32_e32 v46, v46
	v_pk_mul_f32 v[50:51], v[48:49], v[58:59]
	v_mul_f32_e32 v47, 0x3f317217, v46
	v_fma_f32 v47, v46, s95, -v47
	v_add_f32_e32 v50, v69, v50
	v_fmac_f32_e32 v47, 0x3377d1cf, v46
	v_add_f32_e32 v58, v50, v51
	v_pk_mul_f32 v[50:51], v[48:49], v[62:63]
	v_fmac_f32_e32 v47, 0x3f317217, v46
	v_cmp_lt_f32_e64 s[0:1], |v46|, s27
	v_add_f32_e32 v50, v156, v50
	v_add_f32_e32 v55, v50, v51
	v_cndmask_b32_e64 v46, v46, v47, s[0:1]
	v_cndmask_b32_e32 v47, 0, v233, vcc
	v_mov_b32_e32 v50, v52
	v_sub_f32_e32 v52, v46, v47
	v_mul_f32_e64 v47, |v66|, s3
	v_exp_f32_e32 v47, v47
	v_mov_b32_e32 v51, v60
	v_pk_mul_f32 v[50:51], v[48:49], v[50:51]
	v_mov_b32_e32 v60, v53
	v_add_f32_e32 v50, v157, v50
	v_add_f32_e32 v59, v50, v51
	v_pk_mul_f32 v[50:51], v[48:49], v[56:57]
	v_pk_mul_f32 v[48:49], v[48:49], v[60:61]
	v_add_f32_e32 v47, 1.0, v47
	v_add_f32_e32 v48, v159, v48
	v_cmp_gt_f32_e32 vcc, s33, v47
	v_add_f32_e32 v61, v48, v49
	v_add_f32_e32 v50, v158, v50
	v_cndmask_b32_e64 v49, 0, 32, vcc
	v_ldexp_f32 v47, v47, v49
	v_log_f32_e32 v47, v47
	v_add_f32_e32 v57, v50, v51
	v_min_f32_e32 v60, 0, v57
	v_min_f32_e32 v56, 0, v59
	v_mul_f32_e32 v49, 0x3f317217, v47
	v_fma_f32 v49, v47, s95, -v49
	v_fmac_f32_e32 v49, 0x3377d1cf, v47
	v_fmac_f32_e32 v49, 0x3f317217, v47
	v_cmp_lt_f32_e64 s[0:1], |v47|, s27
	v_min_f32_e32 v48, 0, v65
	v_min_f32_e32 v46, 0, v66
	v_cndmask_b32_e64 v47, v47, v49, s[0:1]
	v_cndmask_b32_e32 v49, 0, v233, vcc
	v_sub_f32_e32 v50, v47, v49
	v_mul_f32_e64 v47, |v58|, s3
	v_exp_f32_e32 v47, v47
	v_min_f32_e32 v49, 0, v58
	v_add_f32_e32 v47, 1.0, v47
	v_cmp_gt_f32_e32 vcc, s33, v47
	s_nop 1
	v_cndmask_b32_e64 v51, 0, 32, vcc
	v_ldexp_f32 v47, v47, v51
	v_log_f32_e32 v47, v47
	s_nop 0
	v_mul_f32_e32 v51, 0x3f317217, v47
	v_fma_f32 v51, v47, s95, -v51
	v_fmac_f32_e32 v51, 0x3377d1cf, v47
	v_fmac_f32_e32 v51, 0x3f317217, v47
	v_cmp_lt_f32_e64 s[0:1], |v47|, s27
	s_nop 1
	v_cndmask_b32_e64 v47, v47, v51, s[0:1]
	v_cndmask_b32_e32 v51, 0, v233, vcc
	v_sub_f32_e32 v53, v47, v51
	v_mul_f32_e64 v51, |v55|, s3
	v_exp_f32_e32 v51, v51
	v_min_f32_e32 v47, 0, v55
	v_pk_add_f32 v[48:49], v[48:49], v[52:53] neg_lo:[0,1] neg_hi:[0,1]
	v_add_f32_e32 v51, 1.0, v51
	v_cmp_gt_f32_e32 vcc, s33, v51
	s_nop 1
	v_cndmask_b32_e64 v55, 0, 32, vcc
	v_ldexp_f32 v51, v51, v55
	v_log_f32_e32 v51, v51
	s_nop 0
	v_mul_f32_e32 v55, 0x3f317217, v51
	v_fma_f32 v55, v51, s95, -v55
	v_fmac_f32_e32 v55, 0x3377d1cf, v51
	v_fmac_f32_e32 v55, 0x3f317217, v51
	v_cmp_lt_f32_e64 s[0:1], |v51|, s27
	s_nop 1
	v_cndmask_b32_e64 v51, v51, v55, s[0:1]
	v_cndmask_b32_e32 v55, 0, v233, vcc
	v_sub_f32_e32 v51, v51, v55
	v_mul_f32_e64 v55, |v59|, s3
	v_exp_f32_e32 v55, v55
	v_pk_add_f32 v[46:47], v[46:47], v[50:51] neg_lo:[0,1] neg_hi:[0,1]
	v_add_f32_e32 v55, 1.0, v55
	v_cmp_gt_f32_e32 vcc, s33, v55
	v_pk_mul_f32 v[46:47], v[46:47], s[34:35] op_sel_hi:[1,0]
	s_nop 0
	v_cndmask_b32_e64 v58, 0, 32, vcc
	v_ldexp_f32 v55, v55, v58
	v_log_f32_e32 v55, v55
	s_nop 0
	v_mul_f32_e32 v58, 0x3f317217, v55
	v_fma_f32 v58, v55, s95, -v58
	v_fmac_f32_e32 v58, 0x3377d1cf, v55
	v_fmac_f32_e32 v58, 0x3f317217, v55
	v_cmp_lt_f32_e64 s[0:1], |v55|, s27
	s_nop 1
	v_cndmask_b32_e64 v55, v55, v58, s[0:1]
	v_cndmask_b32_e32 v58, 0, v233, vcc
	v_sub_f32_e32 v58, v55, v58
	v_mul_f32_e64 v55, |v57|, s3
	v_exp_f32_e32 v55, v55
	s_nop 0
	v_add_f32_e32 v55, 1.0, v55
	v_cmp_gt_f32_e32 vcc, s33, v55
	s_nop 1
	v_cndmask_b32_e64 v57, 0, 32, vcc
	v_ldexp_f32 v55, v55, v57
	v_log_f32_e32 v55, v55
	s_nop 0
	v_mul_f32_e32 v57, 0x3f317217, v55
	v_fma_f32 v57, v55, s95, -v57
	v_fmac_f32_e32 v57, 0x3377d1cf, v55
	v_fmac_f32_e32 v57, 0x3f317217, v55
	v_cmp_lt_f32_e64 s[0:1], |v55|, s27
	s_nop 1
	v_cndmask_b32_e64 v55, v55, v57, s[0:1]
	v_cndmask_b32_e32 v57, 0, v233, vcc
	v_sub_f32_e32 v62, v55, v57
	v_mul_f32_e64 v55, |v61|, s3
	v_exp_f32_e32 v55, v55
	v_min_f32_e32 v57, 0, v61
	v_min_f32_e32 v61, 0, v54
	v_add_f32_e32 v55, 1.0, v55
	v_cmp_gt_f32_e32 vcc, s33, v55
	s_nop 1
	v_cndmask_b32_e64 v59, 0, 32, vcc
	v_ldexp_f32 v55, v55, v59
	v_log_f32_e32 v55, v55
	s_nop 0
	v_mul_f32_e32 v59, 0x3f317217, v55
	v_fma_f32 v59, v55, s95, -v59
	v_fmac_f32_e32 v59, 0x3377d1cf, v55
	v_fmac_f32_e32 v59, 0x3f317217, v55
	v_cmp_lt_f32_e64 s[0:1], |v55|, s27
	s_nop 1
	v_cndmask_b32_e64 v55, v55, v59, s[0:1]
	v_cndmask_b32_e32 v59, 0, v233, vcc
	v_sub_f32_e32 v59, v55, v59
	v_pk_add_f32 v[52:53], v[56:57], v[58:59] neg_lo:[0,1] neg_hi:[0,1]
	v_pk_mul_f32 v[56:57], v[48:49], s[34:35] op_sel_hi:[1,0]
	v_mul_f32_e64 v48, |v54|, s3
	v_exp_f32_e32 v48, v48
	v_pk_mul_f32 v[58:59], v[52:53], s[34:35] op_sel_hi:[1,0]
	v_mov_b32_e32 v54, 0
	v_mov_b32_e32 v55, 0
	v_add_f32_e32 v48, 1.0, v48
	v_cmp_gt_f32_e32 vcc, s33, v48
	s_nop 1
	v_cndmask_b32_e64 v49, 0, 32, vcc
	v_ldexp_f32 v48, v48, v49
	v_log_f32_e32 v48, v48
	s_nop 0
	v_mul_f32_e32 v49, 0x3f317217, v48
	v_fma_f32 v49, v48, s95, -v49
	v_fmac_f32_e32 v49, 0x3377d1cf, v48
	v_fmac_f32_e32 v49, 0x3f317217, v48
	v_cmp_lt_f32_e64 s[0:1], |v48|, s27
	s_nop 1
	v_cndmask_b32_e64 v48, v48, v49, s[0:1]
	v_cndmask_b32_e32 v49, 0, v233, vcc
	v_sub_f32_e32 v63, v48, v49
	v_pk_add_f32 v[48:49], v[60:61], v[62:63] neg_lo:[0,1] neg_hi:[0,1]
	s_nop 0
	v_pk_mul_f32 v[48:49], v[48:49], s[34:35] op_sel_hi:[1,0]
	ds_write_b128 v151, v[56:59] offset:8448
	ds_write_b128 v151, v[46:49] offset:8464
	s_waitcnt lgkmcnt(0)
	s_barrier
; #define SEG(src, ld, ktiles, ntiles, n0s, dst, dk, n0d) if (r < (ktiles) * (ntiles)) { const int kt = r / (ntiles), ntl = r % (ntiles); transpose_tile(src, ld, kt * 64, (n0s) + ntl * 64, dst, dk, (n0d) + ntl * 64, tile); continue; } r -= (ktiles) * (ntiles);
; #define LBAR() do { asm volatile("s_waitcnt lgkmcnt(0)" ::: "memory"); __builtin_amdgcn_s_barrier(); asm volatile("" ::: "memory"); } while (0)
; __device__ void gla_item(const Params& P, int l, int b, int h, int seg, LAS unsigned char* lds) {
;     ...
;             const int d = tid & 63, sg = tid >> 6; float cum[8]; float run = 0.f;
; #pragma unroll
;             for (int i = 0; i < 8; ++i) { run += LC[(sg * 8 + i) * 64 + d]; cum[i] = run; }
;             SEG[sg * 64 + d] = run;
;             LBAR();
	ds_read2st64_b32 v[46:47], v152 offset0:33 offset1:34
	ds_read2st64_b32 v[48:49], v152 offset0:35 offset1:36
	ds_read2st64_b32 v[50:51], v152 offset0:37 offset1:38
	ds_read2st64_b32 v[52:53], v152 offset0:39 offset1:40
	s_waitcnt lgkmcnt(3)
	v_add_f32_e32 v46, 0, v46
	v_add_f32_e32 v47, v46, v47
	s_waitcnt lgkmcnt(2)
	v_add_f32_e32 v48, v47, v48
	v_add_f32_e32 v49, v48, v49
	s_waitcnt lgkmcnt(1)
	v_add_f32_e32 v50, v49, v50
	v_add_f32_e32 v51, v50, v51
	s_waitcnt lgkmcnt(0)
	v_add_f32_e32 v52, v51, v52
	v_add_f32_e32 v53, v52, v53
	ds_write_b32 v118, v53 offset:24832
	s_waitcnt lgkmcnt(0)
	s_barrier
	s_and_saveexec_b64 s[0:1], s[40:41]
	s_cbranch_execnz .LBB0_507
	s_or_b64 exec, exec, s[0:1]
	v_mov_b32_e32 v56, 0
	s_and_saveexec_b64 s[0:1], s[42:43]
	s_cbranch_execnz .LBB0_508
